# kernel start: the 18 conditioning-vector loads per thread (SiLU table for the modulation GEMV) issued together with one wait (was an 18-step load-wait ladder)
# speedup vs baseline: 1.0087x; 1.0043x over previous
.LBB0_3:
	s_or_b64 exec, exec, s[2:3]
	v_readlane_b32 s2, v251, 2
	v_readlane_b32 s3, v251, 3
	s_load_dwordx8 s[4:11], s[2:3], 0x40
	v_mov_b32_e32 v1, v128
	s_movk_i32 s2, 0x2400
	s_waitcnt lgkmcnt(0)
	s_barrier
	s_nop 0
	v_cmp_gt_i32_e32 vcc, s2, v1
	v_lshl_add_u32 v6, v1, 2, 0
	s_and_saveexec_b64 s[2:3], vcc
	s_cbranch_execz .LBB0_10
	v_lshlrev_b32_e32 v2, 2, v128
	global_load_dword v10, v2, s[6:7]
	global_load_dword v11, v2, s[6:7] offset:2048
	global_load_dword v12, v2, s[4:5]
	global_load_dword v13, v2, s[4:5] offset:2048
	v_add_u32_e32 v3, 0x1000, v2
	global_load_dword v14, v3, s[4:5]
	v_add_u32_e32 v3, 0x1800, v2
	global_load_dword v15, v3, s[4:5]
	v_add_u32_e32 v3, 0x2000, v2
	global_load_dword v16, v3, s[4:5]
	v_add_u32_e32 v3, 0x2800, v2
	global_load_dword v17, v3, s[4:5]
	v_add_u32_e32 v3, 0x3000, v2
	global_load_dword v18, v3, s[4:5]
	v_add_u32_e32 v3, 0x3800, v2
	global_load_dword v19, v3, s[4:5]
	v_add_u32_e32 v3, 0x4000, v2
	global_load_dword v20, v3, s[4:5]
	v_add_u32_e32 v3, 0x4800, v2
	global_load_dword v21, v3, s[4:5]
	v_add_u32_e32 v3, 0x5000, v2
	global_load_dword v22, v3, s[4:5]
	v_add_u32_e32 v3, 0x5800, v2
	global_load_dword v23, v3, s[4:5]
	v_add_u32_e32 v3, 0x6000, v2
	global_load_dword v24, v3, s[4:5]
	v_add_u32_e32 v3, 0x6800, v2
	global_load_dword v25, v3, s[4:5]
	v_add_u32_e32 v3, 0x7000, v2
	global_load_dword v26, v3, s[4:5]
	v_add_u32_e32 v3, 0x7800, v2
	global_load_dword v27, v3, s[4:5]
	s_waitcnt vmcnt(0)
	v_mul_f32_e32 v28, 0xbfb8aa3b, v10
	v_mul_f32_e32 v29, 0xbfb8aa3b, v11
	v_mul_f32_e32 v30, 0xbfb8aa3b, v12
	v_mul_f32_e32 v31, 0xbfb8aa3b, v13
	v_mul_f32_e32 v32, 0xbfb8aa3b, v14
	v_mul_f32_e32 v33, 0xbfb8aa3b, v15
	v_mul_f32_e32 v34, 0xbfb8aa3b, v16
	v_mul_f32_e32 v35, 0xbfb8aa3b, v17
	v_mul_f32_e32 v36, 0xbfb8aa3b, v18
	v_mul_f32_e32 v37, 0xbfb8aa3b, v19
	v_mul_f32_e32 v38, 0xbfb8aa3b, v20
	v_mul_f32_e32 v39, 0xbfb8aa3b, v21
	v_mul_f32_e32 v40, 0xbfb8aa3b, v22
	v_mul_f32_e32 v41, 0xbfb8aa3b, v23
	v_mul_f32_e32 v42, 0xbfb8aa3b, v24
	v_mul_f32_e32 v43, 0xbfb8aa3b, v25
	v_mul_f32_e32 v44, 0xbfb8aa3b, v26
	v_mul_f32_e32 v45, 0xbfb8aa3b, v27
	v_exp_f32_e32 v28, v28
	v_exp_f32_e32 v29, v29
	v_exp_f32_e32 v30, v30
	v_exp_f32_e32 v31, v31
	v_exp_f32_e32 v32, v32
	v_exp_f32_e32 v33, v33
	v_exp_f32_e32 v34, v34
	v_exp_f32_e32 v35, v35
	v_exp_f32_e32 v36, v36
	v_exp_f32_e32 v37, v37
	v_exp_f32_e32 v38, v38
	v_exp_f32_e32 v39, v39
	v_exp_f32_e32 v40, v40
	v_exp_f32_e32 v41, v41
	v_exp_f32_e32 v42, v42
	v_exp_f32_e32 v43, v43
	v_exp_f32_e32 v44, v44
	v_exp_f32_e32 v45, v45
	v_add_f32_e32 v28, 1.0, v28
	v_add_f32_e32 v29, 1.0, v29
	v_add_f32_e32 v30, 1.0, v30
	v_add_f32_e32 v31, 1.0, v31
	v_add_f32_e32 v32, 1.0, v32
	v_add_f32_e32 v33, 1.0, v33
	v_add_f32_e32 v34, 1.0, v34
	v_add_f32_e32 v35, 1.0, v35
	v_add_f32_e32 v36, 1.0, v36
	v_add_f32_e32 v37, 1.0, v37
	v_add_f32_e32 v38, 1.0, v38
	v_add_f32_e32 v39, 1.0, v39
	v_add_f32_e32 v40, 1.0, v40
	v_add_f32_e32 v41, 1.0, v41
	v_add_f32_e32 v42, 1.0, v42
	v_add_f32_e32 v43, 1.0, v43
	v_add_f32_e32 v44, 1.0, v44
	v_add_f32_e32 v45, 1.0, v45
	v_rcp_f32_e32 v28, v28
	v_rcp_f32_e32 v29, v29
	v_rcp_f32_e32 v30, v30
	v_rcp_f32_e32 v31, v31
	v_rcp_f32_e32 v32, v32
	v_rcp_f32_e32 v33, v33
	v_rcp_f32_e32 v34, v34
	v_rcp_f32_e32 v35, v35
	v_rcp_f32_e32 v36, v36
	v_rcp_f32_e32 v37, v37
	v_rcp_f32_e32 v38, v38
	v_rcp_f32_e32 v39, v39
	v_rcp_f32_e32 v40, v40
	v_rcp_f32_e32 v41, v41
	v_rcp_f32_e32 v42, v42
	v_rcp_f32_e32 v43, v43
	v_rcp_f32_e32 v44, v44
	v_rcp_f32_e32 v45, v45
	v_mul_f32_e32 v10, v10, v28
	v_mul_f32_e32 v11, v11, v29
	v_mul_f32_e32 v12, v12, v30
	v_mul_f32_e32 v13, v13, v31
	v_mul_f32_e32 v14, v14, v32
	v_mul_f32_e32 v15, v15, v33
	v_mul_f32_e32 v16, v16, v34
	v_mul_f32_e32 v17, v17, v35
	v_mul_f32_e32 v18, v18, v36
	v_mul_f32_e32 v19, v19, v37
	v_mul_f32_e32 v20, v20, v38
	v_mul_f32_e32 v21, v21, v39
	v_mul_f32_e32 v22, v22, v40
	v_mul_f32_e32 v23, v23, v41
	v_mul_f32_e32 v24, v24, v42
	v_mul_f32_e32 v25, v25, v43
	v_mul_f32_e32 v26, v26, v44
	v_mul_f32_e32 v27, v27, v45
	ds_write_b32 v6, v10
	ds_write_b32 v6, v11 offset:2048
	ds_write_b32 v6, v12 offset:4096
	ds_write_b32 v6, v13 offset:6144
	ds_write_b32 v6, v14 offset:8192
	ds_write_b32 v6, v15 offset:10240
	ds_write_b32 v6, v16 offset:12288
	ds_write_b32 v6, v17 offset:14336
	ds_write_b32 v6, v18 offset:16384
	ds_write_b32 v6, v19 offset:18432
	ds_write_b32 v6, v20 offset:20480
	ds_write_b32 v6, v21 offset:22528
	ds_write_b32 v6, v22 offset:24576
	ds_write_b32 v6, v23 offset:26624
	ds_write_b32 v6, v24 offset:28672
	ds_write_b32 v6, v25 offset:30720
	ds_write_b32 v6, v26 offset:32768
	ds_write_b32 v6, v27 offset:34816
